# v114 + GEMM8: rounds of 4 M-tiles x 8 N-tiles inside the first 320 tiles of each 352-tile group (A tile fetched once per XCD)
# baseline (speedup 1.0000x reference)
; template <int GI>
; __device__ __forceinline__ bool sched_next(unsigned char* ws, int i, int G, int c, GUnit& u) {
;     ...
;         constexpr int nwg = d.nM * d.nN;
;         if (L >= nwg) return false;
;         int wgid = L;
;         { constexpr int q = nwg / 8, r = nwg % 8; const int xcd = wgid % 8, off = wgid / 8; wgid = (xcd < r ? xcd * (q + 1) : r * (q + 1) + (xcd - r) * q) + off; }
;         constexpr int nig = 8 * d.nN; const int gid = wgid / nig, fm = gid * 8, gsz = (d.nM - fm) < 8 ? (d.nM - fm) : 8;
;         const int pm = fm + ((wgid % nig) % gsz), pn = (wgid % nig) / gsz;
; template <int GI>
; __device__ __forceinline__ void gemm_phase(LAS unsigned char* lds, unsigned char* ws, int G, int cblk) {
;     ...
;     const int tid = tid_, wid = __builtin_amdgcn_readfirstlane(tid >> 6), lane = tid & 63, wr = wid >> 2, wc = wid & 3, fr = lane & 15, fq = lane >> 4;
;     constexpr int K = g.K, nt = K / BK, lda = g.lda, ldb = g.ldb;
;     unsigned voffA[2], voffB[2];
; #pragma unroll
;     for (int i = 0; i < 2; ++i) { int R, C; stage_rc(tid * 16 + i * 8192, R, C); const int Rb = (R & ~31) + perm32(R & 31);
;         voffA[i] = (unsigned)(R * lda + C) * 2u; voffB[i] = (unsigned)(Rb * ldb + C) * 2u; }
;     const size_t kstep = (size_t)(BK * 2);
;     const size_t hstepA = (size_t)HALF * lda * 2, hstepB = (size_t)HALF * ldb * 2;
;     const unsigned ldsw = (unsigned)wid * 1024u;
;     const int aoff = lds_byte(wr * 64 + fr, fq * 8), boff = lds_byte(wc * 32 + fr, fq * 8);
;     ...
;     GUnit cur, nxt; int ui = 0;
;     if (!sched_next<GI>(ws, 0, G, cblk, cur)) return;
;     f32x4 acc[2][2][4][2];
; #pragma unroll
;     for (int a = 0; a < 2; ++a)
; #pragma unroll
;         for (int b = 0; b < 2; ++b)
; #pragma unroll
;             for (int m = 0; m < 4; ++m)
; #pragma unroll
;                 for (int n = 0; n < 2; ++n) acc[a][b][m][n] = (f32x4){0.f, 0.f, 0.f, 0.f};
;     bf16x8 At[4][2], B0[2][2], B1[2][2];
;     const char* cA = cur.A; const char* cB = cur.B;
;     PG8_STAGE(PG8_SB(0, 0), cB, voffB); PG8_STAGE(PG8_SB(0, 1), cB + hstepB, voffB); PG8_STAGE(PG8_SA(0, 0), cA, voffA); PG8_STAGE(PG8_SA(0, 1), cA + hstepA, voffA);
;     if (wr == 1) PG8_BAR;
;     PG8_WAIT_V(2); PG8_BAR;
;     PG8_STAGE(PG8_SB(1, 0), cB + kstep, voffB); PG8_STAGE(PG8_SA(1, 0), cA + kstep, voffA); PG8_STAGE(PG8_SB(1, 1), cB + hstepB + kstep, voffB);
;     PG8_WAIT_V(6); PG8_BAR;
.LBB0_811:
	s_or_b64 exec, exec, s[6:7]
	s_add_u32 s35, s28, 0x16000000
	s_addc_u32 s46, s29, 0
	v_mov_b32_e32 v11, v162
	s_waitcnt lgkmcnt(0)
	s_barrier
	s_cmpk_gt_i32 s2, 0x15ff
	v_readfirstlane_b32 s0, v11
	s_cbranch_scc1 .LBB0_827
	v_lshlrev_b32_e32 v0, 4, v11
	v_add_u32_e32 v1, 0x2000, v0
	v_ashrrev_i32_e32 v2, 31, v1
	v_lshrrev_b32_e32 v2, 22, v2
	v_add_u32_e32 v2, v1, v2
	v_ashrrev_i32_e32 v8, 10, v2
	v_mul_i32_i24_e32 v2, 0x400, v8
	v_sub_u32_e32 v1, v1, v2
	v_lshrrev_b32_e32 v2, 4, v1
	v_bitop3_b32 v1, v2, v1, 32 bitop3:0x6c
	v_ashrrev_i32_e32 v2, 31, v1
	v_lshrrev_b32_e32 v2, 26, v2
	v_add_u32_e32 v2, v1, v2
	v_lshlrev_b32_e32 v3, 3, v8
	v_ashrrev_i32_e32 v9, 6, v2
	v_and_b32_e32 v3, -16, v3
	v_add_u32_e32 v3, v9, v3
	v_and_b32_e32 v4, 3, v9
	s_mov_b32 s6, 0xfffe0
	v_lshrrev_b32_e32 v5, 2, v3
	v_lshlrev_b32_e32 v6, 1, v3
	v_and_b32_e32 v2, 0xc0, v2
	v_and_or_b32 v4, v3, s6, v4
	v_and_b32_e32 v5, 4, v5
	v_and_b32_e32 v6, 24, v6
	v_sub_u32_e32 v1, v1, v2
	v_mov_b32_e32 v2, 1
	v_or3_b32 v4, v4, v5, v6
	v_lshlrev_b32_e32 v5, 5, v8
	v_ashrrev_i16_sdwa v1, v2, sext(v1) dst_sel:DWORD dst_unused:UNUSED_PAD src0_sel:DWORD src1_sel:BYTE_0
	v_and_b32_e32 v5, 32, v5
	v_bfe_i32 v10, v1, 0, 16
	v_add_lshl_u32 v1, v5, v10, 1
	v_lshl_add_u32 v130, v4, 12, v1
	v_lshl_add_u32 v132, v3, 12, v1
	v_bfe_i32 v1, v11, 27, 1
	v_lshrrev_b32_e32 v1, 22, v1
	v_add_u32_e32 v1, v0, v1
	v_and_b32_e32 v1, 0xfffffc00, v1
	v_sub_u32_e32 v0, v0, v1
	v_lshrrev_b32_e32 v1, 4, v0
	v_ashrrev_i32_e32 v3, 31, v11
	v_bitop3_b32 v0, v1, v0, 32 bitop3:0x6c
	v_lshrrev_b32_e32 v3, 26, v3
	v_ashrrev_i32_e32 v1, 31, v0
	v_add_u32_e32 v3, v11, v3
	v_lshrrev_b32_e32 v1, 26, v1
	v_ashrrev_i32_e32 v13, 6, v3
	v_add_u32_e32 v1, v0, v1
	v_lshlrev_b32_e32 v3, 3, v13
	v_ashrrev_i32_e32 v12, 6, v1
	v_and_b32_e32 v3, -16, v3
	v_add_u32_e32 v3, v12, v3
	v_and_b32_e32 v4, 3, v12
	v_and_or_b32 v4, v3, s6, v4
	s_ashr_i32 s6, s2, 31
	s_lshr_b32 s6, s6, 29
	s_add_i32 s6, s2, s6
	s_ashr_i32 s14, s0, 6
	s_ashr_i32 s7, s6, 3
	s_and_b32 s6, s6, -8
	s_ashr_i32 s1, s0, 8
	s_lshl_b32 s26, s14, 10
	s_sub_i32 s6, s2, s6
	s_cmp_lt_i32 s6, 0
	s_movk_i32 s27, 0x2c1
	s_cselect_b32 s8, s27, 0x2c0
	s_mul_i32 s6, s8, s6
	s_add_i32 s6, s6, s7
	s_mul_hi_i32 s7, s6, 0x2e8ba2e9
	s_lshr_b32 s8, s7, 31
	s_ashr_i32 s7, s7, 6
	s_add_i32 s7, s7, s8
	s_lshl_b32 s9, s7, 3
	s_mulk_i32 s7, 0x160
	s_sub_i32 s6, s6, s7
	s_cmpk_lt_u32 s6, 0x140
	s_cbranch_scc0 .Lg8a_skip
	s_and_b32 s7, s6, 3
	s_bfe_u32 s8, s6, 0x10005
	s_lshl_b32 s8, s8, 2
	s_or_b32 s7, s7, s8
	s_bfe_u32 s8, s6, 0x30002
	s_lshl_b32 s8, s8, 3
	s_or_b32 s7, s7, s8
	s_andn2_b32 s6, s6, 63
	s_or_b32 s6, s6, s7
.Lg8a_skip:
	s_sext_i32_i16 s7, s6
	s_bfe_u32 s7, s7, 0x3001c
	s_add_i32 s7, s6, s7
	s_sext_i32_i16 s8, s7
	s_and_b32 s7, s7, 0xfff8
	s_sub_i32 s6, s6, s7
	s_sext_i32_i16 s6, s6
	s_add_i32 s6, s9, s6
	s_ashr_i32 s7, s6, 31
	s_lshr_b32 s8, s8, 3
	s_lshl_b64 s[12:13], s[6:7], 20
	s_add_u32 s40, s3, s12
	s_addc_u32 s41, s54, s13
	v_lshrrev_b32_e32 v5, 2, v3
	v_lshlrev_b32_e32 v6, 1, v3
	v_and_b32_e32 v1, 0xc0, v1
	s_add_u32 s47, s28, 0x4200000
	v_and_b32_e32 v5, 4, v5
	v_and_b32_e32 v6, 24, v6
	v_sub_u32_e32 v0, v0, v1
	s_addc_u32 s48, s29, 0
	s_bfe_i64 s[12:13], s[8:9], 0x100000
	v_or3_b32 v4, v4, v5, v6
	v_lshlrev_b32_e32 v5, 5, v13
	v_ashrrev_i16_sdwa v0, v2, sext(v0) dst_sel:DWORD dst_unused:UNUSED_PAD src0_sel:DWORD src1_sel:BYTE_0
	s_lshl_b64 s[8:9], s[12:13], 20
	v_and_b32_e32 v5, 32, v5
	v_bfe_i32 v14, v0, 0, 16
	s_add_u32 s42, s47, s8
	v_add_lshl_u32 v0, v5, v14, 1
	s_addc_u32 s43, s48, s9
	s_add_i32 s49, s26, 0
	v_lshl_add_u32 v134, v4, 12, v0
	s_add_i32 m0, s49, 0x10000
	v_lshl_add_u32 v136, v3, 12, v0
	global_load_lds_dwordx4 v134, s[42:43]
	s_add_i32 m0, s49, 0x12000
	s_add_u32 s8, s42, 0x80000
	global_load_lds_dwordx4 v130, s[42:43]
	s_addc_u32 s9, s43, 0
	s_add_i32 m0, s49, 0x14000
	s_add_i32 s50, s49, 0x2000
	global_load_lds_dwordx4 v134, s[8:9]
	s_add_i32 m0, s49, 0x16000
	v_mov_b32_e32 v139, 0
	global_load_lds_dwordx4 v130, s[8:9]
	s_mov_b32 m0, s49
	s_add_u32 s8, s40, 0x80000
	global_load_lds_dwordx4 v136, s[40:41]
	s_mov_b32 m0, s50
	s_addc_u32 s9, s41, 0
	s_add_i32 s51, s49, 0x4000
	global_load_lds_dwordx4 v132, s[40:41]
	s_mov_b32 m0, s51
	s_add_i32 s52, s49, 0x6000
	global_load_lds_dwordx4 v136, s[8:9]
	s_mov_b32 m0, s52
	v_mov_b32_e32 v135, v139
	global_load_lds_dwordx4 v132, s[8:9]
	v_mov_b32_e32 v131, v139
	v_mov_b32_e32 v137, v139
	v_mov_b32_e32 v133, v139
	s_cmp_eq_u32 s1, 1
	s_mov_b32 s7, 0
	v_lshl_add_u64 v[6:7], s[42:43], 0, v[134:135]
	v_lshl_add_u64 v[4:5], s[42:43], 0, v[130:131]
	v_lshl_add_u64 v[0:1], s[40:41], 0, v[136:137]
	s_cselect_b64 s[8:9], -1, 0
	s_cmp_lg_u32 s1, 1
	v_lshl_add_u64 v[2:3], s[40:41], 0, v[132:133]
	s_cbranch_scc1 .LBB0_814
	s_barrier

; template <int GI>
; __device__ __forceinline__ bool sched_next(unsigned char* ws, int i, int G, int c, GUnit& u) {
;     ...
;         constexpr int nwg = d.nM * d.nN;
;         if (L >= nwg) return false;
;         int wgid = L;
;         { constexpr int q = nwg / 8, r = nwg % 8; const int xcd = wgid % 8, off = wgid / 8; wgid = (xcd < r ? xcd * (q + 1) : r * (q + 1) + (xcd - r) * q) + off; }
;         constexpr int nig = 8 * d.nN; const int gid = wgid / nig, fm = gid * 8, gsz = (d.nM - fm) < 8 ? (d.nM - fm) : 8;
;         const int pm = fm + ((wgid % nig) % gsz), pn = (wgid % nig) / gsz;
;         u.A = (const char*)ws + d.A + (size_t)pm * d.a_tile;
;         u.B = (const char*)ws + d.B + (size_t)(pm >> 4) * d.b_batch + (size_t)pn * d.b_tile;
;         u.C = (char*)ws + d.C + (size_t)pm * d.c_rt + (size_t)pn * d.c_ct;
; template <int GI>
; __device__ __forceinline__ void gemm_phase(LAS unsigned char* lds, unsigned char* ws, int G, int cblk) {
;     ...
;         const bool has_next = sched_next<GI>(ws, ui + 1, G, cblk, nxt);
;         const char* nA = has_next ? nxt.A : cA; const char* nB = has_next ? nxt.B : cB;
.LBB0_817:
	s_add_i32 s58, s58, 1
	s_mul_i32 s0, s58, s30
	s_add_i32 s0, s0, s2
	s_cmpk_lt_i32 s0, 0x1600
	s_cselect_b64 s[36:37], -1, 0
	s_cmpk_gt_i32 s0, 0x15ff
	s_cbranch_scc1 .LBB0_819
	s_ashr_i32 s1, s0, 31
	s_lshr_b32 s1, s1, 29
	s_add_i32 s1, s0, s1
	s_ashr_i32 s17, s1, 3
	s_and_b32 s1, s1, -8
	s_sub_i32 s0, s0, s1
	s_cmp_lt_i32 s0, 0
	s_cselect_b32 s1, s27, 0x2c0
	s_mul_i32 s0, s1, s0
	s_add_i32 s0, s0, s17
	s_mul_hi_i32 s1, s0, 0x2e8ba2e9
	s_lshr_b32 s17, s1, 31
	s_ashr_i32 s1, s1, 6
	s_add_i32 s1, s1, s17
	s_lshl_b32 s17, s1, 3
	s_mulk_i32 s1, 0x160
	s_sub_i32 s1, s0, s1
	s_cmpk_lt_u32 s1, 0x140
	s_cbranch_scc0 .Lg8b_skip
	s_and_b32 s0, s1, 3
	s_bfe_u32 s18, s1, 0x10005
	s_lshl_b32 s18, s18, 2
	s_or_b32 s0, s0, s18
	s_bfe_u32 s18, s1, 0x30002
	s_lshl_b32 s18, s18, 3
	s_or_b32 s0, s0, s18
	s_andn2_b32 s1, s1, 63
	s_or_b32 s1, s1, s0
.Lg8b_skip:
	s_bfe_u32 s0, s1, 0x3001c
	s_add_i32 s18, s1, s0
	s_sext_i32_i16 s0, s18
	s_and_b32 s18, s18, 0xfff8
	s_sub_i32 s1, s1, s18
	s_sext_i32_i16 s1, s1
	s_add_i32 s22, s17, s1
	s_ashr_i32 s23, s22, 31
	s_lshr_b32 s0, s0, 3
	s_lshl_b64 s[18:19], s[22:23], 20
	s_add_u32 s18, s3, s18
	s_addc_u32 s19, s54, s19
	s_bfe_i64 s[0:1], s[0:1], 0x100000
	s_lshl_b64 s[20:21], s[0:1], 20
	s_add_u32 s20, s47, s20
	s_addc_u32 s21, s48, s21
	s_mul_hi_i32 s17, s22, 0x2c0000
	s_mul_i32 s22, s22, 0x2c0000
	s_add_u32 s22, s35, s22
	s_addc_u32 s17, s46, s17
	s_lshl_b64 s[0:1], s[0:1], 8
	s_add_u32 s22, s22, s0
	s_addc_u32 s23, s17, s1
